# speedup vs baseline: 1.0267x; 1.0059x over previous
; #define WAIT_V(n) asm volatile("s_waitcnt vmcnt(" #n ")" ::: "memory")
; #define WAIT_L(n) asm volatile("s_waitcnt lgkmcnt(" #n ")" ::: "memory")
; #define BAR __builtin_amdgcn_s_barrier()
; __device__ __forceinline__ void phase_attention(const Params& p, char* shmc) {
;     ...
;     for (int s = 0; s < 16; ++s) {
;       if (s >= 9 && s <= 11) { WAIT_V(12); } else { WAIT_V(8); }
;       WAIT_L(0);
;       BAR;
;       if (s + 3 < 16) { ATT_STAGE(cur, (s + 3) & 15); } else { ATT_STAGE(nxt, (s + 3) & 15); }
;       const char* slot = shmc + (s & 3) * 32768;
;       if (s == 8) {
; #pragma unroll
;         for (int kk = 0; kk < 4; ++kk)
;           qn[kk] = *reinterpret_cast<const bf16x8*>(Q + (size_t)(nxt.h0 >> 1) * MTOK * 256 +
;                                                     (size_t)(nxt.tq0 + c) * 256 + hh * 128 + kk * 32 + fq * 8);
;       }
;       if (s < 8) {
;         const int kr = s;
;         bf16x8 kf[2][4];
; #pragma unroll
;         for (int b = 0; b < 2; ++b)
; #pragma unroll
;           for (int kk = 0; kk < 4; ++kk)
;             kf[b][kk] = *reinterpret_cast<const bf16x8*>(slot + (b ? aK1 : aK0) + (kk >> 1) * 8192 + (kk & 1) * 1024);
;         __builtin_amdgcn_s_setprio(1);
; #pragma unroll
;         for (int b = 0; b < 2; ++b) {
;           f32x4 a = f32x4{0.f, 0.f, 0.f, 0.f};
; #pragma unroll
;           for (int kk = 0; kk < 4; ++kk) a = __builtin_amdgcn_mfma_f32_16x16x32_bf16(kf[b][kk], qf[kk], a, 0, 0, 0);
;           sc[kr][b] = a;
;         }
;         __builtin_amdgcn_s_setprio(0);
.LBB0_815:
	s_ashr_i32 s10, s71, 1
	v_mad_i64_i32 v[122:123], s[2:3], s10, v137, v[88:89]
	v_mad_i64_i32 v[152:153], s[2:3], s10, v137, v[86:87]
	s_add_i32 s10, s90, 0xc0
	s_lshl_b64 s[2:3], s[10:11], 9
	s_waitcnt vmcnt(8)
	v_lshl_add_u64 v[18:19], v[152:153], 0, s[2:3]
	s_mov_b32 m0, s94
	s_waitcnt lgkmcnt(0)
	s_barrier
	global_load_lds_dwordx4 v[18:19], off
	v_lshl_add_u64 v[20:21], v[18:19], 0, s[38:39]
	s_mov_b32 m0, s95
	v_add_u32_e32 v160, v134, v139
	global_load_lds_dwordx4 v[20:21], off
	v_lshl_add_u64 v[20:21], v[18:19], 0, s[40:41]
	s_mov_b32 m0, s96
	v_lshl_add_u64 v[18:19], v[18:19], 0, s[42:43]
	global_load_lds_dwordx4 v[20:21], off
	s_mov_b32 m0, s97
	v_add_u32_e32 v166, v134, v140
	global_load_lds_dwordx4 v[18:19], off
	ds_read_b128 v[18:21], v160
	ds_read_b128 v[22:25], v160 offset:1024
	ds_read_b128 v[26:29], v160 offset:8192
	ds_read_b128 v[30:33], v160 offset:9216
	ds_read_b128 v[34:37], v166
	ds_read_b128 v[38:41], v166 offset:1024
	ds_read_b128 v[42:45], v166 offset:8192
	ds_read_b128 v[46:49], v166 offset:9216
	s_setprio 1
	s_waitcnt vmcnt(0) lgkmcnt(0)
	v_mfma_f32_16x16x32_bf16 v[18:21], v[18:21], v[14:17], 0
	v_mfma_f32_16x16x32_bf16 v[18:21], v[22:25], v[10:13], v[18:21]
	v_mfma_f32_16x16x32_bf16 v[18:21], v[26:29], v[6:9], v[18:21]
	v_mfma_f32_16x16x32_bf16 v[74:77], v[30:33], v[2:5], v[18:21]
	v_mfma_f32_16x16x32_bf16 v[18:21], v[34:37], v[14:17], 0
	v_mfma_f32_16x16x32_bf16 v[18:21], v[38:41], v[10:13], v[18:21]
	v_mfma_f32_16x16x32_bf16 v[18:21], v[42:45], v[6:9], v[18:21]
	v_mfma_f32_16x16x32_bf16 v[70:73], v[46:49], v[2:5], v[18:21]
	s_setprio 0
	s_add_i32 s86, s90, 0x100
	s_mov_b32 s87, s11
	s_lshl_b64 s[2:3], s[86:87], 9
	s_mov_b32 m0, s93
	s_waitcnt vmcnt(8)
	s_nop 1
	v_lshl_add_u64 v[18:19], v[152:153], 0, s[2:3]
	s_add_i32 s68, s93, 0x2000
	s_waitcnt lgkmcnt(0)
	s_barrier
	global_load_lds_dwordx4 v[18:19], off
	v_lshl_add_u64 v[20:21], v[18:19], 0, s[38:39]
	s_mov_b32 m0, s68
	s_add_i32 s13, s93, 0x4000
	global_load_lds_dwordx4 v[20:21], off
	v_lshl_add_u64 v[20:21], v[18:19], 0, s[40:41]
	s_mov_b32 m0, s13
	s_add_i32 s2, s93, 0x6000
	global_load_lds_dwordx4 v[20:21], off
	v_lshl_add_u64 v[18:19], v[18:19], 0, s[42:43]
	s_mov_b32 m0, s2
	s_nop 0
	global_load_lds_dwordx4 v[18:19], off
	ds_read_b128 v[18:21], v160 offset:32768
	ds_read_b128 v[22:25], v160 offset:33792
	ds_read_b128 v[26:29], v160 offset:40960
	ds_read_b128 v[30:33], v160 offset:41984
	ds_read_b128 v[34:37], v166 offset:32768
	ds_read_b128 v[38:41], v166 offset:33792
	ds_read_b128 v[42:45], v166 offset:40960
	ds_read_b128 v[46:49], v166 offset:41984
	s_setprio 1
	s_waitcnt lgkmcnt(0)
	v_mfma_f32_16x16x32_bf16 v[18:21], v[18:21], v[14:17], 0
	v_mfma_f32_16x16x32_bf16 v[18:21], v[22:25], v[10:13], v[18:21]
	v_mfma_f32_16x16x32_bf16 v[18:21], v[26:29], v[6:9], v[18:21]
	v_mfma_f32_16x16x32_bf16 v[66:69], v[30:33], v[2:5], v[18:21]
	v_mfma_f32_16x16x32_bf16 v[18:21], v[34:37], v[14:17], 0
	v_mfma_f32_16x16x32_bf16 v[18:21], v[38:41], v[10:13], v[18:21]
	v_mfma_f32_16x16x32_bf16 v[18:21], v[42:45], v[6:9], v[18:21]
	v_mfma_f32_16x16x32_bf16 v[62:65], v[46:49], v[2:5], v[18:21]
	s_setprio 0
	s_add_i32 s84, s90, 0x140
	s_mov_b32 s85, s11
	s_lshl_b64 s[72:73], s[84:85], 9
	s_add_i32 s14, s93, 0x8000
	s_waitcnt vmcnt(8)
	s_nop 1
	v_lshl_add_u64 v[18:19], v[152:153], 0, s[72:73]
	s_mov_b32 m0, s14
	s_add_i32 s69, s93, 0xa000
	s_waitcnt lgkmcnt(0)
	s_barrier
	global_load_lds_dwordx4 v[18:19], off
	v_lshl_add_u64 v[20:21], v[18:19], 0, s[38:39]
	s_mov_b32 m0, s69
	s_add_i32 s70, s93, 0xc000
	global_load_lds_dwordx4 v[20:21], off
	v_lshl_add_u64 v[20:21], v[18:19], 0, s[40:41]
	s_mov_b32 m0, s70
	s_add_i32 s76, s93, 0xe000
	global_load_lds_dwordx4 v[20:21], off
	v_lshl_add_u64 v[18:19], v[18:19], 0, s[42:43]
	s_mov_b32 m0, s76
	v_add_u32_e32 v170, v135, v139
	global_load_lds_dwordx4 v[18:19], off
	v_add_u32_e32 v171, v135, v140
	ds_read_b128 v[18:21], v170
	ds_read_b128 v[22:25], v170 offset:1024
	ds_read_b128 v[26:29], v170 offset:8192
	ds_read_b128 v[30:33], v170 offset:9216
	ds_read_b128 v[34:37], v171
	ds_read_b128 v[38:41], v171 offset:1024
	ds_read_b128 v[42:45], v171 offset:8192
	ds_read_b128 v[46:49], v171 offset:9216
	s_setprio 1
	s_waitcnt lgkmcnt(0)
	v_mfma_f32_16x16x32_bf16 v[18:21], v[18:21], v[14:17], 0
	v_mfma_f32_16x16x32_bf16 v[18:21], v[22:25], v[10:13], v[18:21]
	v_mfma_f32_16x16x32_bf16 v[18:21], v[26:29], v[6:9], v[18:21]
	v_mfma_f32_16x16x32_bf16 v[58:61], v[30:33], v[2:5], v[18:21]
	v_mfma_f32_16x16x32_bf16 v[18:21], v[34:37], v[14:17], 0
	v_mfma_f32_16x16x32_bf16 v[18:21], v[38:41], v[10:13], v[18:21]
	v_mfma_f32_16x16x32_bf16 v[18:21], v[42:45], v[6:9], v[18:21]
	v_mfma_f32_16x16x32_bf16 v[54:57], v[46:49], v[2:5], v[18:21]
	s_setprio 0
	s_add_i32 s82, s90, 0x180
	s_mov_b32 s83, s11
	s_lshl_b64 s[72:73], s[82:83], 9
	s_mov_b32 m0, s34
	s_waitcnt vmcnt(8)
	s_nop 1
	v_lshl_add_u64 v[18:19], v[152:153], 0, s[72:73]
	s_waitcnt lgkmcnt(0)
	s_barrier
; #define WAIT_V(n) asm volatile("s_waitcnt vmcnt(" #n ")" ::: "memory")
; #define WAIT_L(n) asm volatile("s_waitcnt lgkmcnt(" #n ")" ::: "memory")
; #define BAR __builtin_amdgcn_s_barrier()
; __device__ __forceinline__ void phase_attention(const Params& p, char* shmc) {
;     ...
;     for (int s = 0; s < 16; ++s) {
;       if (s >= 9 && s <= 11) { WAIT_V(12); } else { WAIT_V(8); }
;       WAIT_L(0);
;       BAR;
;       if (s + 3 < 16) { ATT_STAGE(cur, (s + 3) & 15); } else { ATT_STAGE(nxt, (s + 3) & 15); }
;       const char* slot = shmc + (s & 3) * 32768;
;       if (s == 8) {
; #pragma unroll
;         for (int kk = 0; kk < 4; ++kk)
;           qn[kk] = *reinterpret_cast<const bf16x8*>(Q + (size_t)(nxt.h0 >> 1) * MTOK * 256 +
;                                                     (size_t)(nxt.tq0 + c) * 256 + hh * 128 + kk * 32 + fq * 8);
;       }
;       if (s < 8) {
;         const int kr = s;
;         bf16x8 kf[2][4];
; #pragma unroll
;         for (int b = 0; b < 2; ++b)
; #pragma unroll
;           for (int kk = 0; kk < 4; ++kk)
;             kf[b][kk] = *reinterpret_cast<const bf16x8*>(slot + (b ? aK1 : aK0) + (kk >> 1) * 8192 + (kk & 1) * 1024);
;         __builtin_amdgcn_s_setprio(1);
; #pragma unroll
;         for (int b = 0; b < 2; ++b) {
;           f32x4 a = f32x4{0.f, 0.f, 0.f, 0.f};
; #pragma unroll
;           for (int kk = 0; kk < 4; ++kk) a = __builtin_amdgcn_mfma_f32_16x16x32_bf16(kf[b][kk], qf[kk], a, 0, 0, 0);
;           sc[kr][b] = a;
;         }
;         __builtin_amdgcn_s_setprio(0);
	global_load_lds_dwordx4 v[18:19], off
	v_lshl_add_u64 v[20:21], v[18:19], 0, s[38:39]
	s_mov_b32 m0, s35
	v_add_u32_e32 v174, v136, v139
	global_load_lds_dwordx4 v[20:21], off
	v_lshl_add_u64 v[20:21], v[18:19], 0, s[40:41]
	s_mov_b32 m0, s6
	v_lshl_add_u64 v[18:19], v[18:19], 0, s[42:43]
	global_load_lds_dwordx4 v[20:21], off
	s_mov_b32 m0, s7
	v_add_u32_e32 v178, v136, v140
	global_load_lds_dwordx4 v[18:19], off
	ds_read_b128 v[18:21], v174
	ds_read_b128 v[22:25], v174 offset:1024
	ds_read_b128 v[26:29], v174 offset:8192
	ds_read_b128 v[30:33], v174 offset:9216
	ds_read_b128 v[34:37], v178
	ds_read_b128 v[38:41], v178 offset:1024
	ds_read_b128 v[42:45], v178 offset:8192
	ds_read_b128 v[46:49], v178 offset:9216
	s_setprio 1
	s_waitcnt lgkmcnt(0)
	v_mfma_f32_16x16x32_bf16 v[18:21], v[18:21], v[14:17], 0
	v_mfma_f32_16x16x32_bf16 v[18:21], v[22:25], v[10:13], v[18:21]
	v_mfma_f32_16x16x32_bf16 v[18:21], v[26:29], v[6:9], v[18:21]
	v_mfma_f32_16x16x32_bf16 v[50:53], v[30:33], v[2:5], v[18:21]
	v_mfma_f32_16x16x32_bf16 v[18:21], v[34:37], v[14:17], 0
	v_mfma_f32_16x16x32_bf16 v[18:21], v[38:41], v[10:13], v[18:21]
	v_mfma_f32_16x16x32_bf16 v[18:21], v[42:45], v[6:9], v[18:21]
	v_mfma_f32_16x16x32_bf16 v[46:49], v[46:49], v[2:5], v[18:21]
	s_setprio 0
	s_add_i32 s80, s90, 0x1c0
	s_mov_b32 s81, s11
	s_lshl_b64 s[72:73], s[80:81], 9
	s_mov_b32 m0, s94
	s_waitcnt vmcnt(8)
	s_nop 1
	v_lshl_add_u64 v[18:19], v[152:153], 0, s[72:73]
	s_waitcnt lgkmcnt(0)
	s_barrier
	global_load_lds_dwordx4 v[18:19], off
	v_lshl_add_u64 v[20:21], v[18:19], 0, s[38:39]
	s_mov_b32 m0, s95
	s_nop 0
	global_load_lds_dwordx4 v[20:21], off
	v_lshl_add_u64 v[20:21], v[18:19], 0, s[40:41]
	s_mov_b32 m0, s96
	v_lshl_add_u64 v[18:19], v[18:19], 0, s[42:43]
	global_load_lds_dwordx4 v[20:21], off
	s_mov_b32 m0, s97
	s_nop 0
	global_load_lds_dwordx4 v[18:19], off
	ds_read_b128 v[18:21], v160
	ds_read_b128 v[22:25], v160 offset:1024
	ds_read_b128 v[26:29], v160 offset:8192
	ds_read_b128 v[30:33], v160 offset:9216
	ds_read_b128 v[34:37], v166
	ds_read_b128 v[38:41], v166 offset:1024
	ds_read_b128 v[152:155], v166 offset:8192
	ds_read_b128 v[156:159], v166 offset:9216
	s_setprio 1
	s_waitcnt lgkmcnt(0)
	v_mfma_f32_16x16x32_bf16 v[18:21], v[18:21], v[14:17], 0
	v_mfma_f32_16x16x32_bf16 v[18:21], v[22:25], v[10:13], v[18:21]
	v_mfma_f32_16x16x32_bf16 v[18:21], v[26:29], v[6:9], v[18:21]
	v_mfma_f32_16x16x32_bf16 v[42:45], v[30:33], v[2:5], v[18:21]
	v_mfma_f32_16x16x32_bf16 v[18:21], v[34:37], v[14:17], 0
	v_mfma_f32_16x16x32_bf16 v[18:21], v[38:41], v[10:13], v[18:21]
	v_mfma_f32_16x16x32_bf16 v[18:21], v[152:155], v[6:9], v[18:21]
	v_mfma_f32_16x16x32_bf16 v[34:37], v[156:159], v[2:5], v[18:21]
	s_setprio 0
	s_mov_b32 s91, s11
	s_lshl_b64 s[72:73], s[90:91], 9
	s_waitcnt vmcnt(8)
	s_nop 3
	v_lshl_add_u64 v[18:19], v[122:123], 0, s[72:73]
	s_mov_b32 m0, s93
	s_waitcnt lgkmcnt(0)
	s_barrier
	global_load_lds_dwordx4 v[18:19], off
	v_lshl_add_u64 v[20:21], v[18:19], 0, s[48:49]
	s_mov_b32 m0, s68
	s_mul_i32 s3, s5, 0x7c
	global_load_lds_dwordx4 v[20:21], off
	v_lshl_add_u64 v[20:21], v[18:19], 0, s[52:53]
	s_mov_b32 m0, s13
	v_lshl_add_u64 v[18:19], v[18:19], 0, s[54:55]
	global_load_lds_dwordx4 v[20:21], off
	s_mov_b32 m0, s2
	v_add_u32_e32 v152, s3, v125
	global_load_lds_dwordx4 v[18:19], off
	ds_read_b128 v[18:21], v160 offset:32768
	ds_read_b128 v[22:25], v160 offset:33792
	ds_read_b128 v[26:29], v160 offset:40960
	ds_read_b128 v[30:33], v160 offset:41984
	ds_read_b128 v[154:157], v166 offset:32768
	ds_read_b128 v[158:161], v166 offset:33792
	ds_read_b128 v[162:165], v166 offset:40960
	ds_read_b128 v[166:169], v166 offset:41984
	v_lshl_add_u32 v121, v141, 2, v152
	s_setprio 1
	s_waitcnt lgkmcnt(0)
	v_mfma_f32_16x16x32_bf16 v[18:21], v[18:21], v[14:17], 0
	v_mfma_f32_16x16x32_bf16 v[18:21], v[22:25], v[10:13], v[18:21]
	v_mfma_f32_16x16x32_bf16 v[18:21], v[26:29], v[6:9], v[18:21]
	v_mfma_f32_16x16x32_bf16 v[38:41], v[30:33], v[2:5], v[18:21]
	v_mfma_f32_16x16x32_bf16 v[18:21], v[154:157], v[14:17], 0
	v_mfma_f32_16x16x32_bf16 v[18:21], v[158:161], v[10:13], v[18:21]
	v_mfma_f32_16x16x32_bf16 v[18:21], v[162:165], v[6:9], v[18:21]
	v_mfma_f32_16x16x32_bf16 v[30:33], v[166:169], v[2:5], v[18:21]
	s_setprio 0
	s_add_i32 s72, s90, 64
	s_ashr_i32 s73, s72, 31
	s_lshl_b64 s[72:73], s[72:73], 9
	s_mov_b32 m0, s14
	s_waitcnt vmcnt(8)
	s_nop 1
	v_lshl_add_u64 v[18:19], v[122:123], 0, s[72:73]
	s_waitcnt lgkmcnt(0)
	s_barrier
	global_load_lds_dwordx4 v[18:19], off
	v_lshl_add_u64 v[20:21], v[18:19], 0, s[48:49]
	s_mov_b32 m0, s69
	s_nop 0
	global_load_lds_dwordx4 v[20:21], off
	v_lshl_add_u64 v[20:21], v[18:19], 0, s[52:53]
	s_mov_b32 m0, s70
	v_lshl_add_u64 v[18:19], v[18:19], 0, s[54:55]
	global_load_lds_dwordx4 v[20:21], off
	s_mov_b32 m0, s76
	s_nop 0
	global_load_lds_dwordx4 v[18:19], off
	ds_read_b128 v[18:21], v170
	ds_read_b128 v[22:25], v170 offset:1024
	ds_read_b128 v[26:29], v170 offset:8192
	ds_read_b128 v[154:157], v170 offset:9216
	ds_read_b128 v[158:161], v171
	ds_read_b128 v[162:165], v171 offset:1024
	ds_read_b128 v[166:169], v171 offset:8192
	ds_read_b128 v[170:173], v171 offset:9216
	s_setprio 1
	s_waitcnt lgkmcnt(0)
	v_mfma_f32_16x16x32_bf16 v[18:21], v[18:21], v[14:17], 0
	v_mfma_f32_16x16x32_bf16 v[18:21], v[22:25], v[10:13], v[18:21]
	v_mfma_f32_16x16x32_bf16 v[18:21], v[26:29], v[6:9], v[18:21]
	v_mfma_f32_16x16x32_bf16 v[26:29], v[154:157], v[2:5], v[18:21]
	v_mfma_f32_16x16x32_bf16 v[18:21], v[158:161], v[14:17], 0
	v_mfma_f32_16x16x32_bf16 v[18:21], v[162:165], v[10:13], v[18:21]
	v_mfma_f32_16x16x32_bf16 v[18:21], v[166:169], v[6:9], v[18:21]
	v_mfma_f32_16x16x32_bf16 v[22:25], v[170:173], v[2:5], v[18:21]
	s_setprio 0
	s_add_i32 s72, s90, 0x80
	s_ashr_i32 s73, s72, 31
	s_lshl_b64 s[72:73], s[72:73], 9
	s_mov_b32 m0, s34
	s_waitcnt vmcnt(8)
	s_nop 1
	v_lshl_add_u64 v[18:19], v[122:123], 0, s[72:73]
	s_waitcnt lgkmcnt(0)
	s_barrier
; __device__ __forceinline__ void phase_attention(const Params& p, char* shmc) {
;     ...
;         __builtin_amdgcn_s_setprio(1);
; #pragma unroll
;         for (int b = 0; b < 2; ++b) {
;           f32x4 a = f32x4{0.f, 0.f, 0.f, 0.f};
; #pragma unroll
;           for (int kk = 0; kk < 4; ++kk) a = __builtin_amdgcn_mfma_f32_16x16x32_bf16(kf[b][kk], qf[kk], a, 0, 0, 0);
;           sc[kr][b] = a;
;         }
;         __builtin_amdgcn_s_setprio(0);
;         if (s == 7) {
;           const int cstart = min(max(c - 8, 0), 48);
;           float mx = -1e30f;
; #pragma unroll
;           for (int k2 = 0; k2 < 8; ++k2) {
;             const float* brow_ = bias_lds + (cur.dr + k2) * 31 + 15;
; #pragma unroll
;             for (int b = 0; b < 2; ++b)
; #pragma unroll
;               for (int j = 0; j < 4; ++j) {
;                 const int kc = cw0 + fq * 8 + b * 4 + j;
;                 const bool valid = (kc >= cstart) && (kc < cstart + 16);
;                 const int dc = min(max(kc - c, -15), 15);
;                 const float sv = valid ? (sc[k2][b][j] + brow_[dc]) : -1e30f;
;                 sc[k2][b][j] = sv;
;                 mx = fmaxf(mx, sv);
;               }
;           }
	global_load_lds_dwordx4 v[18:19], off
	v_lshl_add_u64 v[20:21], v[18:19], 0, s[48:49]
	s_mov_b32 m0, s35
	s_nop 0
	global_load_lds_dwordx4 v[20:21], off
	v_lshl_add_u64 v[20:21], v[18:19], 0, s[52:53]
	s_mov_b32 m0, s6
	v_lshl_add_u64 v[18:19], v[18:19], 0, s[54:55]
	global_load_lds_dwordx4 v[20:21], off
	s_mov_b32 m0, s7
	s_nop 0
	global_load_lds_dwordx4 v[18:19], off
	ds_read_b128 v[18:21], v174
	ds_read_b128 v[154:157], v174 offset:1024
	ds_read_b128 v[158:161], v174 offset:8192
	ds_read_b128 v[162:165], v174 offset:9216
	ds_read_b128 v[166:169], v178
	ds_read_b128 v[170:173], v178 offset:1024
	ds_read_b128 v[174:177], v178 offset:8192
	ds_read_b128 v[178:181], v178 offset:9216
	s_setprio 1
	s_waitcnt lgkmcnt(0)
	v_mfma_f32_16x16x32_bf16 v[18:21], v[18:21], v[14:17], 0
	v_mfma_f32_16x16x32_bf16 v[14:17], v[166:169], v[14:17], 0
	v_mfma_f32_16x16x32_bf16 v[18:21], v[154:157], v[10:13], v[18:21]
	v_mfma_f32_16x16x32_bf16 v[10:13], v[170:173], v[10:13], v[14:17]
	v_mfma_f32_16x16x32_bf16 v[18:21], v[158:161], v[6:9], v[18:21]
	v_mfma_f32_16x16x32_bf16 v[6:9], v[174:177], v[6:9], v[10:13]
	v_mfma_f32_16x16x32_bf16 v[18:21], v[162:165], v[2:5], v[18:21]
	v_mfma_f32_16x16x32_bf16 v[2:5], v[178:181], v[2:5], v[6:9]
	s_setprio 0
	s_nop 4
	v_mov_b32_e32 v6, 0xf149f2ca
	v_mov_b32_e32 v7, 0xf149f2ca
	ds_read_b32 v214, v121 offset:928
	v_cndmask_b32_e64 v7, v7, v74, s[56:57]
	v_lshl_add_u32 v74, v142, 2, v152
	ds_read_b32 v215, v74 offset:928
	v_cndmask_b32_e64 v6, v6, v75, s[58:59]
	v_lshl_add_u32 v75, v143, 2, v152
	v_mov_b32_e32 v8, 0xf149f2ca
	v_mov_b32_e32 v9, 0xf149f2ca
	ds_read_b32 v216, v75 offset:928
	v_cndmask_b32_e64 v9, v9, v76, s[60:61]
	v_lshl_add_u32 v76, v144, 2, v152
	ds_read_b32 v217, v76 offset:928
	v_cndmask_b32_e64 v8, v8, v77, s[62:63]
	v_lshl_add_u32 v77, v145, 2, v152
	v_mov_b32_e32 v10, 0xf149f2ca
	v_mov_b32_e32 v11, 0xf149f2ca
	ds_read_b32 v218, v77 offset:928
	v_cndmask_b32_e64 v11, v11, v70, s[64:65]
	v_lshl_add_u32 v70, v146, 2, v152
	ds_read_b32 v219, v70 offset:928
	v_cndmask_b32_e64 v10, v10, v71, s[66:67]
	v_lshl_add_u32 v71, v147, 2, v152
	v_mov_b32_e32 v12, 0xf149f2ca
	v_mov_b32_e32 v13, 0xf149f2ca
	ds_read_b32 v220, v71 offset:928
	v_cndmask_b32_e64 v13, v13, v72, s[78:79]
	v_lshl_add_u32 v72, v148, 2, v152
	ds_read_b32 v221, v72 offset:928
	v_cndmask_b32_e64 v12, v12, v73, s[0:1]
	v_mov_b32_e32 v14, 0xf149f2ca
	v_mov_b32_e32 v15, 0xf149f2ca
	ds_read_b32 v222, v121 offset:1052
	v_cndmask_b32_e64 v15, v15, v66, s[56:57]
	ds_read_b32 v223, v74 offset:1052
	v_cndmask_b32_e64 v14, v14, v67, s[58:59]
	v_mov_b32_e32 v16, 0xf149f2ca
	v_mov_b32_e32 v17, 0xf149f2ca
	ds_read_b32 v224, v75 offset:1052
	v_cndmask_b32_e64 v17, v17, v68, s[60:61]
	ds_read_b32 v225, v76 offset:1052
	v_cndmask_b32_e64 v16, v16, v69, s[62:63]
	v_mov_b32_e32 v66, 0xf149f2ca
	v_mov_b32_e32 v67, 0xf149f2ca
	ds_read_b32 v226, v77 offset:1052
	v_cndmask_b32_e64 v67, v67, v62, s[64:65]
	ds_read_b32 v227, v70 offset:1052
	v_cndmask_b32_e64 v66, v66, v63, s[66:67]
	v_mov_b32_e32 v62, 0xf149f2ca
	v_mov_b32_e32 v63, 0xf149f2ca
	ds_read_b32 v228, v71 offset:1052
	v_cndmask_b32_e64 v63, v63, v64, s[78:79]
	ds_read_b32 v229, v72 offset:1052
	v_cndmask_b32_e64 v62, v62, v65, s[0:1]
	s_waitcnt lgkmcnt(8)
	v_add_f32_e32 v7, v7, v214
	v_add_f32_e32 v6, v6, v215
	v_add_f32_e32 v9, v9, v216
	v_add_f32_e32 v8, v8, v217
	v_add_f32_e32 v11, v11, v218
	v_add_f32_e32 v10, v10, v219
	v_add_f32_e32 v13, v13, v220
	v_add_f32_e32 v12, v12, v221
	v_mov_b32_e32 v64, 0xf149f2ca
	v_mov_b32_e32 v65, 0xf149f2ca
	ds_read_b32 v214, v121 offset:1176
	v_cndmask_b32_e64 v65, v65, v58, s[56:57]
	ds_read_b32 v215, v74 offset:1176
	v_cndmask_b32_e64 v64, v64, v59, s[58:59]
	v_mov_b32_e32 v58, 0xf149f2ca
	v_mov_b32_e32 v59, 0xf149f2ca
	ds_read_b32 v216, v75 offset:1176
	v_cndmask_b32_e64 v59, v59, v60, s[60:61]
	ds_read_b32 v217, v76 offset:1176
	v_cndmask_b32_e64 v58, v58, v61, s[62:63]
	v_mov_b32_e32 v60, 0xf149f2ca
	v_mov_b32_e32 v61, 0xf149f2ca
	ds_read_b32 v218, v77 offset:1176
	v_cndmask_b32_e64 v61, v61, v54, s[64:65]
	ds_read_b32 v219, v70 offset:1176
	v_cndmask_b32_e64 v60, v60, v55, s[66:67]
	v_mov_b32_e32 v54, 0xf149f2ca
	v_mov_b32_e32 v55, 0xf149f2ca
	ds_read_b32 v220, v71 offset:1176
	v_cndmask_b32_e64 v55, v55, v56, s[78:79]
	ds_read_b32 v221, v72 offset:1176
	v_cndmask_b32_e64 v54, v54, v57, s[0:1]
	s_waitcnt lgkmcnt(8)
	v_add_f32_e32 v15, v15, v222
	v_add_f32_e32 v14, v14, v223
	v_add_f32_e32 v17, v17, v224
	v_add_f32_e32 v16, v16, v225
	v_add_f32_e32 v67, v67, v226
	v_add_f32_e32 v66, v66, v227
	v_add_f32_e32 v63, v63, v228
	v_add_f32_e32 v62, v62, v229
	v_mov_b32_e32 v56, 0xf149f2ca
	v_mov_b32_e32 v57, 0xf149f2ca
	ds_read_b32 v222, v121 offset:1300
	v_cndmask_b32_e64 v57, v57, v50, s[56:57]
	ds_read_b32 v223, v74 offset:1300
	v_cndmask_b32_e64 v56, v56, v51, s[58:59]
	v_mov_b32_e32 v50, 0xf149f2ca
	v_mov_b32_e32 v51, 0xf149f2ca
	ds_read_b32 v224, v75 offset:1300
	v_cndmask_b32_e64 v51, v51, v52, s[60:61]
	ds_read_b32 v225, v76 offset:1300
	v_cndmask_b32_e64 v50, v50, v53, s[62:63]
	v_mov_b32_e32 v52, 0xf149f2ca
	v_mov_b32_e32 v53, 0xf149f2ca
	ds_read_b32 v226, v77 offset:1300
	v_cndmask_b32_e64 v53, v53, v46, s[64:65]
	ds_read_b32 v227, v70 offset:1300
	v_cndmask_b32_e64 v52, v52, v47, s[66:67]
	v_mov_b32_e32 v46, 0xf149f2ca
	v_mov_b32_e32 v47, 0xf149f2ca
	ds_read_b32 v228, v71 offset:1300
	v_cndmask_b32_e64 v47, v47, v48, s[78:79]
	ds_read_b32 v229, v72 offset:1300
	v_cndmask_b32_e64 v46, v46, v49, s[0:1]
	s_waitcnt lgkmcnt(8)
; __device__ __forceinline__ void phase_attention(const Params& p, char* shmc) {
;     ...
; #pragma unroll
;           for (int k2 = 0; k2 < 8; ++k2) {
;             const float* brow_ = bias_lds + (cur.dr + k2) * 31 + 15;
; #pragma unroll
;             for (int b = 0; b < 2; ++b)
; #pragma unroll
;               for (int j = 0; j < 4; ++j) {
;                 const int kc = cw0 + fq * 8 + b * 4 + j;
;                 const bool valid = (kc >= cstart) && (kc < cstart + 16);
;                 const int dc = min(max(kc - c, -15), 15);
;                 const float sv = valid ? (sc[k2][b][j] + brow_[dc]) : -1e30f;
;                 sc[k2][b][j] = sv;
;                 mx = fmaxf(mx, sv);
;               }
;           }
	v_add_f32_e32 v65, v65, v214
	v_add_f32_e32 v64, v64, v215
	v_add_f32_e32 v59, v59, v216
	v_add_f32_e32 v58, v58, v217
	v_add_f32_e32 v61, v61, v218
	v_add_f32_e32 v60, v60, v219
	v_add_f32_e32 v55, v55, v220
	v_add_f32_e32 v54, v54, v221
	v_mov_b32_e32 v48, 0xf149f2ca
	v_mov_b32_e32 v49, 0xf149f2ca
	ds_read_b32 v214, v121 offset:1424
	v_cndmask_b32_e64 v49, v49, v42, s[56:57]
	ds_read_b32 v215, v74 offset:1424
	v_cndmask_b32_e64 v48, v48, v43, s[58:59]
	v_mov_b32_e32 v42, 0xf149f2ca
	v_mov_b32_e32 v43, 0xf149f2ca
	ds_read_b32 v216, v75 offset:1424
	v_cndmask_b32_e64 v43, v43, v44, s[60:61]
	ds_read_b32 v217, v76 offset:1424
	v_cndmask_b32_e64 v42, v42, v45, s[62:63]
	v_mov_b32_e32 v44, 0xf149f2ca
	v_mov_b32_e32 v45, 0xf149f2ca
	ds_read_b32 v218, v77 offset:1424
	v_cndmask_b32_e64 v45, v45, v34, s[64:65]
	ds_read_b32 v219, v70 offset:1424
	v_cndmask_b32_e64 v44, v44, v35, s[66:67]
	v_mov_b32_e32 v34, 0xf149f2ca
	v_mov_b32_e32 v35, 0xf149f2ca
	ds_read_b32 v220, v71 offset:1424
	v_cndmask_b32_e64 v35, v35, v36, s[78:79]
	ds_read_b32 v221, v72 offset:1424
	v_cndmask_b32_e64 v34, v34, v37, s[0:1]
	s_waitcnt lgkmcnt(8)
	v_add_f32_e32 v57, v57, v222
	v_add_f32_e32 v56, v56, v223
	v_add_f32_e32 v51, v51, v224
	v_add_f32_e32 v50, v50, v225
	v_add_f32_e32 v53, v53, v226
	v_add_f32_e32 v52, v52, v227
	v_add_f32_e32 v47, v47, v228
	v_add_f32_e32 v46, v46, v229
	v_mov_b32_e32 v36, 0xf149f2ca
	v_mov_b32_e32 v37, 0xf149f2ca
	ds_read_b32 v222, v121 offset:1548
	v_cndmask_b32_e64 v37, v37, v38, s[56:57]
	ds_read_b32 v223, v74 offset:1548
	v_cndmask_b32_e64 v36, v36, v39, s[58:59]
	v_mov_b32_e32 v38, 0xf149f2ca
	v_mov_b32_e32 v39, 0xf149f2ca
	ds_read_b32 v224, v75 offset:1548
	v_cndmask_b32_e64 v39, v39, v40, s[60:61]
	ds_read_b32 v225, v76 offset:1548
	v_cndmask_b32_e64 v38, v38, v41, s[62:63]
	v_mov_b32_e32 v40, 0xf149f2ca
	v_mov_b32_e32 v158, 0xf149f2ca
	ds_read_b32 v226, v77 offset:1548
	v_cndmask_b32_e64 v158, v158, v30, s[64:65]
	ds_read_b32 v227, v70 offset:1548
	v_cndmask_b32_e64 v40, v40, v31, s[66:67]
	v_mov_b32_e32 v30, 0xf149f2ca
	v_mov_b32_e32 v31, 0xf149f2ca
	ds_read_b32 v228, v71 offset:1548
	v_cndmask_b32_e64 v31, v31, v32, s[78:79]
	ds_read_b32 v229, v72 offset:1548
	v_cndmask_b32_e64 v30, v30, v33, s[0:1]
	s_waitcnt lgkmcnt(8)
	v_add_f32_e32 v49, v49, v214
	v_add_f32_e32 v48, v48, v215
	v_add_f32_e32 v43, v43, v216
	v_add_f32_e32 v42, v42, v217
	v_add_f32_e32 v45, v45, v218
	v_add_f32_e32 v44, v44, v219
	v_add_f32_e32 v35, v35, v220
	v_add_f32_e32 v34, v34, v221
	v_mov_b32_e32 v32, 0xf149f2ca
	v_mov_b32_e32 v33, 0xf149f2ca
	ds_read_b32 v214, v121 offset:1672
	v_cndmask_b32_e64 v33, v33, v26, s[56:57]
	ds_read_b32 v215, v74 offset:1672
	v_cndmask_b32_e64 v32, v32, v27, s[58:59]
	v_mov_b32_e32 v26, 0xf149f2ca
	v_mov_b32_e32 v27, 0xf149f2ca
	ds_read_b32 v216, v75 offset:1672
	v_cndmask_b32_e64 v27, v27, v28, s[60:61]
	ds_read_b32 v217, v76 offset:1672
	v_cndmask_b32_e64 v26, v26, v29, s[62:63]
	v_mov_b32_e32 v28, 0xf149f2ca
	v_mov_b32_e32 v29, 0xf149f2ca
	ds_read_b32 v218, v77 offset:1672
	v_cndmask_b32_e64 v29, v29, v22, s[64:65]
	ds_read_b32 v219, v70 offset:1672
	v_cndmask_b32_e64 v28, v28, v23, s[66:67]
	v_mov_b32_e32 v159, 0xf149f2ca
	v_mov_b32_e32 v160, 0xf149f2ca
	ds_read_b32 v220, v71 offset:1672
	v_cndmask_b32_e64 v160, v160, v24, s[78:79]
	ds_read_b32 v221, v72 offset:1672
	v_cndmask_b32_e64 v159, v159, v25, s[0:1]
	s_waitcnt lgkmcnt(8)
	v_add_f32_e32 v37, v37, v222
	v_add_f32_e32 v36, v36, v223
	v_add_f32_e32 v39, v39, v224
	v_add_f32_e32 v38, v38, v225
	v_add_f32_e32 v158, v158, v226
	v_add_f32_e32 v40, v40, v227
	v_add_f32_e32 v31, v31, v228
	v_add_f32_e32 v30, v30, v229
	v_mov_b32_e32 v24, 0xf149f2ca
	v_mov_b32_e32 v25, 0xf149f2ca
	ds_read_b32 v222, v121 offset:1796
	v_cndmask_b32_e64 v25, v25, v18, s[56:57]
	ds_read_b32 v223, v74 offset:1796
	v_cndmask_b32_e64 v24, v24, v19, s[58:59]
	v_mov_b32_e32 v161, 0xf149f2ca
	v_mov_b32_e32 v162, 0xf149f2ca
	ds_read_b32 v224, v75 offset:1796
	v_cndmask_b32_e64 v162, v162, v20, s[60:61]
	ds_read_b32 v225, v76 offset:1796
	v_cndmask_b32_e64 v161, v161, v21, s[62:63]
	v_mov_b32_e32 v163, 0xf149f2ca
	v_mov_b32_e32 v164, 0xf149f2ca
	ds_read_b32 v226, v77 offset:1796
	v_cndmask_b32_e64 v164, v164, v2, s[64:65]
	ds_read_b32 v227, v70 offset:1796
	v_cndmask_b32_e64 v163, v163, v3, s[66:67]
	v_mov_b32_e32 v165, 0xf149f2ca
	v_mov_b32_e32 v166, 0xf149f2ca
	ds_read_b32 v228, v71 offset:1796
	v_cndmask_b32_e64 v166, v166, v4, s[78:79]
	ds_read_b32 v229, v72 offset:1796
	v_cndmask_b32_e64 v165, v165, v5, s[0:1]
	s_waitcnt lgkmcnt(8)
	v_add_f32_e32 v33, v33, v214
	v_add_f32_e32 v32, v32, v215
	v_add_f32_e32 v27, v27, v216
	v_add_f32_e32 v26, v26, v217
	v_add_f32_e32 v29, v29, v218
	v_add_f32_e32 v28, v28, v219
	v_add_f32_e32 v160, v160, v220
	v_add_f32_e32 v159, v159, v221
	s_waitcnt lgkmcnt(0)
; __device__ __forceinline__ AttItem att_item(int item) {
;   constexpr int NROWS = 768;
;   const int hp = item / NROWS, R = item % NROWS;
;   int s0, rows, r;
;   if (R < 256) { s0 = 0; rows = 256; r = R; }
;   else { int b = (R - 256) >> 7; s0 = NPROMPT + b * SSEQ; rows = 128; r = (R - 256) & 127; }
;   const int rs = min(max(r - 4, 0), rows - 8);
;   AttItem it;
;   it.rowtok0 = s0 + rs * 64; it.h0 = hp * 2; it.dr = rs - r + 7; it.tq0 = s0 + r * 64;
;   return it;
; __device__ __forceinline__ void phase_attention(const Params& p, char* shmc) {
;     ...
;           mx = fmaxf(mx, __shfl_xor(mx, 16));
;           mx = fmaxf(mx, __shfl_xor(mx, 32));
; #pragma unroll
;           for (int k2 = 0; k2 < 8; ++k2)
; #pragma unroll
;             for (int b = 0; b < 2; ++b)
; #pragma unroll
;               for (int j = 0; j < 4; ++j) {
;                 const float e = __expf(sc[k2][b][j] - mx);
;                 sc[k2][b][j] = e;
;                 sum += e;
;               }
;           sum += __shfl_xor(sum, 16);
;           sum += __shfl_xor(sum, 32);
	v_add_f32_e32 v25, v25, v222
	v_add_f32_e32 v24, v24, v223
	v_add_f32_e32 v162, v162, v224
	v_add_f32_e32 v161, v161, v225
	v_add_f32_e32 v164, v164, v226
	v_add_f32_e32 v163, v163, v227
	v_add_f32_e32 v166, v166, v228
	v_add_f32_e32 v165, v165, v229
	s_mov_b32 s3, 0xf149f2ca
	v_max3_f32 v2, v7, s3, v6
	v_max3_f32 v2, v2, v9, v8
	v_max3_f32 v2, v2, v11, v10
	v_max3_f32 v2, v2, v13, v12
	v_max3_f32 v2, v2, v15, v14
	v_max3_f32 v2, v2, v17, v16
	v_max3_f32 v2, v2, v67, v66
	v_max3_f32 v2, v2, v63, v62
	v_max3_f32 v2, v2, v65, v64
	v_max3_f32 v2, v2, v59, v58
	v_max3_f32 v2, v2, v61, v60
	v_max3_f32 v2, v2, v55, v54
	s_add_i32 s3, s4, s15
	v_max3_f32 v2, v2, v57, v56
	s_cmpk_gt_i32 s3, 0x17ff
	v_max3_f32 v2, v2, v51, v50
	s_cselect_b64 s[88:89], -1, 0
	s_cmpk_lt_i32 s3, 0x1800
	v_max3_f32 v2, v2, v53, v52
	s_cselect_b32 s4, s3, s4
	v_max3_f32 v2, v2, v47, v46
	s_mul_hi_i32 s5, s4, 0x2aaaaaab
	v_max3_f32 v2, v2, v49, v48
	s_lshr_b32 s12, s5, 31
	s_ashr_i32 s5, s5, 7
	v_max3_f32 v2, v2, v43, v42
	s_add_i32 s5, s5, s12
	v_max3_f32 v2, v2, v45, v44
	s_mul_i32 s12, s5, 0x300
	v_max3_f32 v2, v2, v35, v34
	s_sub_i32 s4, s4, s12
	v_max3_f32 v2, v2, v37, v36
	s_lshl_b32 s12, s4, 6
	v_max3_f32 v2, v2, v39, v38
	s_add_i32 s12, s12, 0x7fffc000
	v_max3_f32 v2, v2, v158, v40
	s_and_b32 s12, s12, 0x7fffe000
	v_max3_f32 v2, v2, v31, v30
	s_and_b32 s72, s4, 0x7f
	s_add_i32 s73, s12, 0x4000
	v_max3_f32 v2, v2, v33, v32
	s_cmpk_lt_i32 s4, 0x100
	v_max3_f32 v2, v2, v27, v26
	s_cselect_b32 s12, s4, s72
	v_max3_f32 v2, v2, v29, v28
	s_cselect_b32 s4, s33, 0x78
	s_cselect_b32 s90, 0, s73
	s_max_i32 s72, s12, 4
	v_max3_f32 v2, v2, v160, v159
	s_add_i32 s72, s72, -4
	v_max3_f32 v2, v2, v25, v24
	s_min_u32 s4, s72, s4
	s_lshl_b32 s72, s12, 6
	v_max3_f32 v2, v2, v162, v161
	s_add_i32 s77, s90, s72
	v_max3_f32 v18, v2, v164, v163
	s_lshl_b32 s91, s4, 6
	s_mul_i32 s75, s5, 0x1800000
	v_mad_i64_i32 v[22:23], s[72:73], s5, v137, v[86:87]
	v_or_b32_e32 v2, s77, v130
	s_mul_hi_i32 s74, s5, 0x1800000
	s_add_u32 s72, s28, s75
	v_ashrrev_i32_e32 v3, 31, v2
	s_addc_u32 s73, s29, s74
	v_lshlrev_b64 v[2:3], 9, v[2:3]
	v_lshl_add_u64 v[2:3], s[72:73], 0, v[2:3]
	v_lshl_add_u64 v[2:3], v[2:3], 0, v[84:85]
	v_lshlrev_b32_e32 v4, 1, v80
	v_mov_b32_e32 v5, v85
	v_lshl_add_u64 v[2:3], v[2:3], 0, v[4:5]
	v_max3_f32 v4, v18, v166, v165
	v_and_b32_e32 v18, 64, v138
	v_xor_b32_e32 v5, 16, v138
	v_add_u32_e32 v18, 64, v18
	v_cmp_lt_i32_e32 vcc, v5, v18
	s_ashr_i32 s73, s10, 31
	s_mov_b32 s72, s10
	v_cndmask_b32_e32 v5, v138, v5, vcc
	v_lshlrev_b32_e32 v5, 2, v5
	ds_bpermute_b32 v19, v5, v4
	s_lshl_b64 s[72:73], s[72:73], 9
	s_waitcnt vmcnt(8)
	s_mov_b32 m0, s94
	s_waitcnt lgkmcnt(0)
	s_waitcnt lgkmcnt(0)
	v_max_f32_e32 v19, v19, v19
	v_max_f32_e32 v4, v4, v19
	v_xor_b32_e32 v19, 32, v138
	v_cmp_lt_i32_e32 vcc, v19, v18
	s_barrier
	s_nop 0
	v_cndmask_b32_e32 v18, v138, v19, vcc
	v_lshlrev_b32_e32 v167, 2, v18
	ds_bpermute_b32 v18, v167, v4
	s_waitcnt lgkmcnt(0)
	v_max_f32_e32 v18, v18, v18
	v_max_f32_e32 v4, v4, v18
	v_sub_f32_e32 v7, v7, v4
	v_mul_f32_e32 v7, 0x3fb8aa3b, v7
	v_sub_f32_e32 v6, v6, v4
	v_exp_f32_e32 v18, v7
	v_mul_f32_e32 v6, 0x3fb8aa3b, v6
	v_exp_f32_e32 v19, v6
	v_add_f32_e32 v7, 0, v18
	v_add_f32_e32 v6, v19, v7
	v_sub_f32_e32 v7, v9, v4
	v_mul_f32_e32 v7, 0x3fb8aa3b, v7
	v_exp_f32_e32 v20, v7
	v_sub_f32_e32 v7, v8, v4
	v_mul_f32_e32 v7, 0x3fb8aa3b, v7
	v_exp_f32_e32 v21, v7
	v_sub_f32_e32 v7, v11, v4
	v_mul_f32_e32 v7, 0x3fb8aa3b, v7
	v_exp_f32_e32 v154, v7
	v_sub_f32_e32 v7, v10, v4
	v_mul_f32_e32 v7, 0x3fb8aa3b, v7
	v_exp_f32_e32 v155, v7
	v_sub_f32_e32 v7, v13, v4
	v_mul_f32_e32 v7, 0x3fb8aa3b, v7
	v_exp_f32_e32 v156, v7
	v_sub_f32_e32 v7, v12, v4
	v_mul_f32_e32 v7, 0x3fb8aa3b, v7
	v_exp_f32_e32 v157, v7
	v_sub_f32_e32 v7, v15, v4
	v_mul_f32_e32 v7, 0x3fb8aa3b, v7
	v_exp_f32_e32 v73, v7
	v_sub_f32_e32 v7, v14, v4
	v_mul_f32_e32 v7, 0x3fb8aa3b, v7
	v_exp_f32_e32 v74, v7
	v_sub_f32_e32 v7, v17, v4
	v_mul_f32_e32 v7, 0x3fb8aa3b, v7
	v_exp_f32_e32 v75, v7
	v_sub_f32_e32 v7, v16, v4
	v_mul_f32_e32 v7, 0x3fb8aa3b, v7
	v_exp_f32_e32 v76, v7
	v_sub_f32_e32 v7, v67, v4
	v_mul_f32_e32 v7, 0x3fb8aa3b, v7
	v_exp_f32_e32 v77, v7
	v_sub_f32_e32 v7, v66, v4
	v_mul_f32_e32 v7, 0x3fb8aa3b, v7
	v_exp_f32_e32 v121, v7
	v_sub_f32_e32 v7, v63, v4
	v_mul_f32_e32 v7, 0x3fb8aa3b, v7
	v_exp_f32_e32 v152, v7
	v_sub_f32_e32 v7, v62, v4
	v_mul_f32_e32 v7, 0x3fb8aa3b, v7
	v_exp_f32_e32 v153, v7
	v_sub_f32_e32 v7, v65, v4
	v_mul_f32_e32 v7, 0x3fb8aa3b, v7
	v_exp_f32_e32 v65, v7
	v_sub_f32_e32 v7, v64, v4
	v_mul_f32_e32 v7, 0x3fb8aa3b, v7
	v_exp_f32_e32 v66, v7
	v_sub_f32_e32 v7, v59, v4
	v_mul_f32_e32 v7, 0x3fb8aa3b, v7
	v_exp_f32_e32 v67, v7
	v_sub_f32_e32 v7, v58, v4
	v_mul_f32_e32 v7, 0x3fb8aa3b, v7
	v_exp_f32_e32 v68, v7
	v_sub_f32_e32 v7, v61, v4
	v_mul_f32_e32 v7, 0x3fb8aa3b, v7
	v_exp_f32_e32 v69, v7
	v_sub_f32_e32 v7, v60, v4
	v_mul_f32_e32 v7, 0x3fb8aa3b, v7
	v_exp_f32_e32 v70, v7
	v_sub_f32_e32 v7, v55, v4
	v_mul_f32_e32 v7, 0x3fb8aa3b, v7
	v_exp_f32_e32 v71, v7
	v_sub_f32_e32 v7, v54, v4
	v_mul_f32_e32 v7, 0x3fb8aa3b, v7
	v_exp_f32_e32 v72, v7
	v_sub_f32_e32 v7, v57, v4
	v_mul_f32_e32 v7, 0x3fb8aa3b, v7
	v_exp_f32_e32 v57, v7
	v_sub_f32_e32 v7, v56, v4
	v_mul_f32_e32 v7, 0x3fb8aa3b, v7
	v_exp_f32_e32 v58, v7
	v_sub_f32_e32 v7, v51, v4
	v_mul_f32_e32 v7, 0x3fb8aa3b, v7
	v_exp_f32_e32 v59, v7
	v_sub_f32_e32 v7, v50, v4
	v_mul_f32_e32 v7, 0x3fb8aa3b, v7
	v_exp_f32_e32 v60, v7
	v_sub_f32_e32 v7, v53, v4
	v_mul_f32_e32 v7, 0x3fb8aa3b, v7
	v_exp_f32_e32 v61, v7
	v_sub_f32_e32 v7, v52, v4
	v_mul_f32_e32 v7, 0x3fb8aa3b, v7
	v_exp_f32_e32 v62, v7
	v_sub_f32_e32 v7, v47, v4
	v_mul_f32_e32 v7, 0x3fb8aa3b, v7
; __device__ __forceinline__ void phase_attention(const Params& p, char* shmc) {
;     ...
; #pragma unroll
;           for (int k2 = 0; k2 < 8; ++k2)
; #pragma unroll
;             for (int b = 0; b < 2; ++b)
; #pragma unroll
;               for (int j = 0; j < 4; ++j) {
;                 const float e = __expf(sc[k2][b][j] - mx);
;                 sc[k2][b][j] = e;
;                 sum += e;
;               }
;           sum += __shfl_xor(sum, 16);
;           sum += __shfl_xor(sum, 32);
;         }
;       } else {
;         const int kr = s - 8;
;         union { bf16x8 v; unsigned u[4]; } pf;
;         pf.u[0] = pack2(sc[kr][0][0], sc[kr][0][1]);
;         pf.u[1] = pack2(sc[kr][0][2], sc[kr][0][3]);
;         pf.u[2] = pack2(sc[kr][1][0], sc[kr][1][1]);
;         pf.u[3] = pack2(sc[kr][1][2], sc[kr][1][3]);
;         bf16x8 vf[8];
; #pragma unroll
;         for (int db = 0; db < 8; ++db) vf[db] = *reinterpret_cast<const bf16x8*>(slot + aV + db * 2048);
;         __builtin_amdgcn_s_setprio(1);
; #pragma unroll
;         for (int db = 0; db < 8; ++db) o[db] = __builtin_amdgcn_mfma_f32_16x16x32_bf16(vf[db], pf.v, o[db], 0, 0, 0);
	v_exp_f32_e32 v63, v7
	v_sub_f32_e32 v7, v46, v4
	v_mul_f32_e32 v7, 0x3fb8aa3b, v7
	v_exp_f32_e32 v64, v7
	v_sub_f32_e32 v7, v49, v4
	v_mul_f32_e32 v7, 0x3fb8aa3b, v7
	v_exp_f32_e32 v49, v7
	v_sub_f32_e32 v7, v48, v4
	v_mul_f32_e32 v7, 0x3fb8aa3b, v7
	v_exp_f32_e32 v50, v7
	v_sub_f32_e32 v7, v43, v4
	v_mul_f32_e32 v7, 0x3fb8aa3b, v7
	v_add_f32_e32 v6, v20, v6
	v_exp_f32_e32 v51, v7
	v_sub_f32_e32 v7, v42, v4
	v_add_f32_e32 v6, v21, v6
	v_mul_f32_e32 v7, 0x3fb8aa3b, v7
	v_add_f32_e32 v6, v154, v6
	v_exp_f32_e32 v52, v7
	v_sub_f32_e32 v7, v45, v4
	v_add_f32_e32 v6, v155, v6
	v_mul_f32_e32 v7, 0x3fb8aa3b, v7
	v_add_f32_e32 v6, v156, v6
	v_exp_f32_e32 v53, v7
	v_sub_f32_e32 v7, v44, v4
	v_add_f32_e32 v6, v157, v6
	v_mul_f32_e32 v7, 0x3fb8aa3b, v7
	v_add_f32_e32 v6, v73, v6
	v_exp_f32_e32 v54, v7
	v_sub_f32_e32 v7, v35, v4
	v_add_f32_e32 v6, v74, v6
	v_mul_f32_e32 v7, 0x3fb8aa3b, v7
	v_add_f32_e32 v6, v75, v6
	v_exp_f32_e32 v55, v7
	v_sub_f32_e32 v7, v34, v4
	v_add_f32_e32 v6, v76, v6
	v_mul_f32_e32 v7, 0x3fb8aa3b, v7
	v_add_f32_e32 v6, v77, v6
	v_exp_f32_e32 v56, v7
	v_sub_f32_e32 v7, v37, v4
	v_add_f32_e32 v6, v121, v6
	v_mul_f32_e32 v7, 0x3fb8aa3b, v7
	v_add_f32_e32 v6, v152, v6
	v_exp_f32_e32 v41, v7
	v_sub_f32_e32 v7, v36, v4
	v_add_f32_e32 v6, v153, v6
	v_mul_f32_e32 v7, 0x3fb8aa3b, v7
	v_add_f32_e32 v6, v65, v6
	v_exp_f32_e32 v42, v7
	v_sub_f32_e32 v7, v39, v4
	v_add_f32_e32 v6, v66, v6
	v_mul_f32_e32 v7, 0x3fb8aa3b, v7
	v_add_f32_e32 v6, v67, v6
	v_exp_f32_e32 v43, v7
	v_sub_f32_e32 v7, v38, v4
	v_add_f32_e32 v6, v68, v6
	v_mul_f32_e32 v7, 0x3fb8aa3b, v7
	v_add_f32_e32 v6, v69, v6
	v_exp_f32_e32 v44, v7
	v_sub_f32_e32 v7, v158, v4
	v_add_f32_e32 v6, v70, v6
	v_mul_f32_e32 v7, 0x3fb8aa3b, v7
	v_add_f32_e32 v6, v71, v6
	v_exp_f32_e32 v45, v7
	v_sub_f32_e32 v7, v40, v4
	v_add_f32_e32 v6, v72, v6
	v_mul_f32_e32 v7, 0x3fb8aa3b, v7
	v_add_f32_e32 v6, v57, v6
	v_exp_f32_e32 v46, v7
	v_sub_f32_e32 v7, v31, v4
	v_add_f32_e32 v6, v58, v6
	v_mul_f32_e32 v7, 0x3fb8aa3b, v7
	v_add_f32_e32 v6, v59, v6
	v_exp_f32_e32 v47, v7
	v_sub_f32_e32 v7, v30, v4
	v_add_f32_e32 v6, v60, v6
	v_mul_f32_e32 v7, 0x3fb8aa3b, v7
	v_add_f32_e32 v6, v61, v6
	v_exp_f32_e32 v48, v7
	v_sub_f32_e32 v7, v33, v4
	v_add_f32_e32 v6, v62, v6
	v_mul_f32_e32 v7, 0x3fb8aa3b, v7
	v_add_f32_e32 v6, v63, v6
	v_exp_f32_e32 v33, v7
	v_sub_f32_e32 v7, v32, v4
	v_add_f32_e32 v6, v64, v6
	v_mul_f32_e32 v7, 0x3fb8aa3b, v7
	v_add_f32_e32 v6, v49, v6
	v_exp_f32_e32 v34, v7
	v_sub_f32_e32 v7, v27, v4
	v_add_f32_e32 v6, v50, v6
	v_mul_f32_e32 v7, 0x3fb8aa3b, v7
	v_add_f32_e32 v6, v51, v6
	v_exp_f32_e32 v35, v7
	v_sub_f32_e32 v7, v26, v4
	v_add_f32_e32 v6, v52, v6
	v_mul_f32_e32 v7, 0x3fb8aa3b, v7
	v_add_f32_e32 v6, v53, v6
	v_exp_f32_e32 v36, v7
	v_sub_f32_e32 v7, v29, v4
	v_add_f32_e32 v6, v54, v6
	v_mul_f32_e32 v7, 0x3fb8aa3b, v7
	v_add_f32_e32 v6, v55, v6
	v_exp_f32_e32 v37, v7
	v_sub_f32_e32 v7, v28, v4
	v_add_f32_e32 v6, v56, v6
	v_mul_f32_e32 v7, 0x3fb8aa3b, v7
	v_add_f32_e32 v6, v41, v6
	v_exp_f32_e32 v38, v7
	v_sub_f32_e32 v7, v160, v4
	v_add_f32_e32 v6, v42, v6
	v_mul_f32_e32 v7, 0x3fb8aa3b, v7
	v_add_f32_e32 v6, v43, v6
	v_exp_f32_e32 v39, v7
	v_sub_f32_e32 v7, v159, v4
	v_add_f32_e32 v6, v44, v6
	v_mul_f32_e32 v7, 0x3fb8aa3b, v7
	v_add_f32_e32 v6, v45, v6
	v_exp_f32_e32 v40, v7
	v_sub_f32_e32 v7, v25, v4
	v_add_f32_e32 v6, v46, v6
	v_mul_f32_e32 v7, 0x3fb8aa3b, v7
	v_add_f32_e32 v6, v47, v6
	v_exp_f32_e32 v25, v7
	v_sub_f32_e32 v7, v24, v4
	v_add_f32_e32 v6, v48, v6
	v_mul_f32_e32 v7, 0x3fb8aa3b, v7
	v_add_f32_e32 v6, v33, v6
	v_exp_f32_e32 v26, v7
	v_sub_f32_e32 v7, v162, v4
	v_add_f32_e32 v6, v34, v6
	v_mul_f32_e32 v7, 0x3fb8aa3b, v7
	v_add_f32_e32 v6, v35, v6
	v_exp_f32_e32 v27, v7
	v_sub_f32_e32 v7, v161, v4
	v_add_f32_e32 v6, v36, v6
	v_mul_f32_e32 v7, 0x3fb8aa3b, v7
	v_add_f32_e32 v6, v37, v6
	v_exp_f32_e32 v28, v7
	v_sub_f32_e32 v7, v164, v4
	v_add_f32_e32 v6, v38, v6
	v_mul_f32_e32 v7, 0x3fb8aa3b, v7
	v_add_f32_e32 v6, v39, v6
	v_exp_f32_e32 v29, v7
	v_sub_f32_e32 v7, v163, v4
	v_add_f32_e32 v6, v40, v6
	v_mul_f32_e32 v7, 0x3fb8aa3b, v7
	v_add_f32_e32 v6, v25, v6
	v_exp_f32_e32 v30, v7
	v_sub_f32_e32 v7, v166, v4
	v_add_f32_e32 v6, v26, v6
	v_mul_f32_e32 v7, 0x3fb8aa3b, v7
	v_sub_f32_e32 v4, v165, v4
	v_add_f32_e32 v6, v27, v6
	v_exp_f32_e32 v31, v7
	v_mul_f32_e32 v4, 0x3fb8aa3b, v4
	v_add_f32_e32 v6, v28, v6
	v_exp_f32_e32 v32, v4
	v_add_f32_e32 v6, v29, v6
	v_add_f32_e32 v6, v30, v6
	v_add_f32_e32 v6, v31, v6
	v_add_f32_e32 v4, v32, v6
	ds_bpermute_b32 v5, v5, v4
	v_cvt_pk_bf16_f32 v18, v18, v19
	v_cvt_pk_bf16_f32 v19, v20, v21
	v_cvt_pk_bf16_f32 v20, v154, v155
	v_cvt_pk_bf16_f32 v21, v156, v157
	s_waitcnt lgkmcnt(0)
	v_add_f32_e32 v4, v4, v5
	ds_bpermute_b32 v5, v167, v4
	s_waitcnt lgkmcnt(0)
	v_add_f32_e32 v24, v4, v5
	v_lshl_add_u64 v[4:5], v[122:123], 0, s[72:73]
	global_load_lds_dwordx4 v[4:5], off
	v_lshl_add_u64 v[6:7], v[4:5], 0, s[48:49]
	s_mov_b32 m0, s95
	s_nop 0
	global_load_lds_dwordx4 v[6:7], off
	v_lshl_add_u64 v[6:7], v[4:5], 0, s[52:53]
	s_mov_b32 m0, s96
	v_lshl_add_u64 v[4:5], v[4:5], 0, s[54:55]
	global_load_lds_dwordx4 v[6:7], off
	s_mov_b32 m0, s97
	s_nop 0
	global_load_lds_dwordx4 v[4:5], off
	global_load_dwordx4 v[14:17], v[2:3], off
	global_load_dwordx4 v[10:13], v[2:3], off offset:64
	global_load_dwordx4 v[6:9], v[2:3], off offset:128
	s_nop 0
	global_load_dwordx4 v[2:5], v[2:3], off offset:192
	ds_read_b128 v[154:157], v149
	ds_read_b128 v[158:161], v149 offset:2048
	ds_read_b128 v[162:165], v149 offset:4096
	ds_read_b128 v[166:169], v149 offset:6144
	ds_read_b128 v[170:173], v149 offset:8192
	ds_read_b128 v[174:177], v149 offset:10240
	ds_read_b128 v[178:181], v149 offset:12288
	ds_read_b128 v[182:185], v149 offset:14336
	s_setprio 1
	s_waitcnt lgkmcnt(0)
	v_mfma_f32_16x16x32_bf16 v[154:157], v[154:157], v[18:21], 0
	v_mfma_f32_16x16x32_bf16 v[158:161], v[158:161], v[18:21], 0
	v_mfma_f32_16x16x32_bf16 v[162:165], v[162:165], v[18:21], 0
	v_mfma_f32_16x16x32_bf16 v[166:169], v[166:169], v[18:21], 0
	v_mfma_f32_16x16x32_bf16 v[170:173], v[170:173], v[18:21], 0
	v_mfma_f32_16x16x32_bf16 v[174:177], v[174:177], v[18:21], 0
	v_mfma_f32_16x16x32_bf16 v[178:181], v[178:181], v[18:21], 0
	v_mfma_f32_16x16x32_bf16 v[18:21], v[182:185], v[18:21], 0
	s_setprio 0
	s_ashr_i32 s87, s86, 31
	s_lshl_b64 s[72:73], s[86:87], 9
	s_waitcnt vmcnt(12)
	v_lshl_add_u64 v[182:183], v[122:123], 0, s[72:73]
	s_mov_b32 m0, s93
	s_waitcnt lgkmcnt(0)
	s_barrier
; #define WAIT_V(n) asm volatile("s_waitcnt vmcnt(" #n ")" ::: "memory")
; #define WAIT_L(n) asm volatile("s_waitcnt lgkmcnt(" #n ")" ::: "memory")
; #define BAR __builtin_amdgcn_s_barrier()
; __device__ __forceinline__ void phase_attention(const Params& p, char* shmc) {
;     ...
;       if (s >= 9 && s <= 11) { WAIT_V(12); } else { WAIT_V(8); }
;       WAIT_L(0);
;       BAR;
;       if (s + 3 < 16) { ATT_STAGE(cur, (s + 3) & 15); } else { ATT_STAGE(nxt, (s + 3) & 15); }
;       const char* slot = shmc + (s & 3) * 32768;
;     ...
;       } else {
;         const int kr = s - 8;
;         union { bf16x8 v; unsigned u[4]; } pf;
;         pf.u[0] = pack2(sc[kr][0][0], sc[kr][0][1]);
;         pf.u[1] = pack2(sc[kr][0][2], sc[kr][0][3]);
;         pf.u[2] = pack2(sc[kr][1][0], sc[kr][1][1]);
;         pf.u[3] = pack2(sc[kr][1][2], sc[kr][1][3]);
;         bf16x8 vf[8];
; #pragma unroll
;         for (int db = 0; db < 8; ++db) vf[db] = *reinterpret_cast<const bf16x8*>(slot + aV + db * 2048);
;         __builtin_amdgcn_s_setprio(1);
; #pragma unroll
;         for (int db = 0; db < 8; ++db) o[db] = __builtin_amdgcn_mfma_f32_16x16x32_bf16(vf[db], pf.v, o[db], 0, 0, 0);
;         __builtin_amdgcn_s_setprio(0);
	global_load_lds_dwordx4 v[182:183], off
	v_lshl_add_u64 v[184:185], v[182:183], 0, s[48:49]
	s_mov_b32 m0, s68
	v_cvt_pk_bf16_f32 v74, v73, v74
	global_load_lds_dwordx4 v[184:185], off
	v_lshl_add_u64 v[184:185], v[182:183], 0, s[52:53]
	s_mov_b32 m0, s13
	v_lshl_add_u64 v[182:183], v[182:183], 0, s[54:55]
	global_load_lds_dwordx4 v[184:185], off
	s_mov_b32 m0, s2
	v_cvt_pk_bf16_f32 v75, v75, v76
	global_load_lds_dwordx4 v[182:183], off
	ds_read_b128 v[182:185], v149 offset:32768
	ds_read_b128 v[186:189], v149 offset:34816
	ds_read_b128 v[190:193], v149 offset:36864
	ds_read_b128 v[194:197], v149 offset:38912
	ds_read_b128 v[198:201], v149 offset:40960
	ds_read_b128 v[202:205], v149 offset:43008
	ds_read_b128 v[206:209], v149 offset:45056
	ds_read_b128 v[210:213], v149 offset:47104
	v_cvt_pk_bf16_f32 v76, v77, v121
	v_cvt_pk_bf16_f32 v77, v152, v153
	s_setprio 1
	s_waitcnt lgkmcnt(0)
	v_mfma_f32_16x16x32_bf16 v[152:155], v[182:185], v[74:77], v[154:157]
	v_mfma_f32_16x16x32_bf16 v[156:159], v[186:189], v[74:77], v[158:161]
	v_mfma_f32_16x16x32_bf16 v[160:163], v[190:193], v[74:77], v[162:165]
	v_mfma_f32_16x16x32_bf16 v[164:167], v[194:197], v[74:77], v[166:169]
	v_mfma_f32_16x16x32_bf16 v[168:171], v[198:201], v[74:77], v[170:173]
	v_mfma_f32_16x16x32_bf16 v[172:175], v[202:205], v[74:77], v[174:177]
	v_mfma_f32_16x16x32_bf16 v[176:179], v[206:209], v[74:77], v[178:181]
	v_mfma_f32_16x16x32_bf16 v[18:21], v[210:213], v[74:77], v[18:21]
	s_setprio 0
	s_ashr_i32 s85, s84, 31
	s_lshl_b64 s[72:73], s[84:85], 9
	s_waitcnt vmcnt(12)
	v_lshl_add_u64 v[74:75], v[122:123], 0, s[72:73]
	s_mov_b32 m0, s14
	s_waitcnt lgkmcnt(0)
	s_barrier
	global_load_lds_dwordx4 v[74:75], off
	v_lshl_add_u64 v[76:77], v[74:75], 0, s[48:49]
	s_mov_b32 m0, s69
	v_cvt_pk_bf16_f32 v67, v67, v68
	global_load_lds_dwordx4 v[76:77], off
	v_lshl_add_u64 v[76:77], v[74:75], 0, s[52:53]
	s_mov_b32 m0, s70
	v_lshl_add_u64 v[74:75], v[74:75], 0, s[54:55]
	global_load_lds_dwordx4 v[76:77], off
	s_mov_b32 m0, s76
	v_cvt_pk_bf16_f32 v68, v69, v70
	global_load_lds_dwordx4 v[74:75], off
	v_cvt_pk_bf16_f32 v69, v71, v72
	ds_read_b128 v[70:73], v150
	ds_read_b128 v[74:77], v150 offset:2048
	ds_read_b128 v[180:183], v150 offset:4096
	ds_read_b128 v[184:187], v150 offset:6144
	ds_read_b128 v[188:191], v150 offset:8192
	ds_read_b128 v[192:195], v150 offset:10240
	ds_read_b128 v[196:199], v150 offset:12288
	ds_read_b128 v[200:203], v150 offset:14336
	v_cvt_pk_bf16_f32 v66, v65, v66
	s_setprio 1
	s_waitcnt lgkmcnt(0)
	v_mfma_f32_16x16x32_bf16 v[70:73], v[70:73], v[66:69], v[152:155]
	v_mfma_f32_16x16x32_bf16 v[74:77], v[74:77], v[66:69], v[156:159]
	v_mfma_f32_16x16x32_bf16 v[152:155], v[180:183], v[66:69], v[160:163]
	v_mfma_f32_16x16x32_bf16 v[156:159], v[184:187], v[66:69], v[164:167]
	v_mfma_f32_16x16x32_bf16 v[160:163], v[188:191], v[66:69], v[168:171]
	v_mfma_f32_16x16x32_bf16 v[164:167], v[192:195], v[66:69], v[172:175]
	v_mfma_f32_16x16x32_bf16 v[168:171], v[196:199], v[66:69], v[176:179]
	v_mfma_f32_16x16x32_bf16 v[18:21], v[200:203], v[66:69], v[18:21]
	s_setprio 0
	s_ashr_i32 s83, s82, 31
	s_lshl_b64 s[72:73], s[82:83], 9
	s_waitcnt vmcnt(12)
	v_lshl_add_u64 v[66:67], v[122:123], 0, s[72:73]
	s_mov_b32 m0, s34
	s_waitcnt lgkmcnt(0)
	s_barrier
	global_load_lds_dwordx4 v[66:67], off
	v_lshl_add_u64 v[68:69], v[66:67], 0, s[48:49]
	s_mov_b32 m0, s35
	v_cvt_pk_bf16_f32 v59, v59, v60
	global_load_lds_dwordx4 v[68:69], off
	v_lshl_add_u64 v[68:69], v[66:67], 0, s[52:53]
	s_mov_b32 m0, s6
	v_lshl_add_u64 v[66:67], v[66:67], 0, s[54:55]
	global_load_lds_dwordx4 v[68:69], off
	s_mov_b32 m0, s7
	v_cvt_pk_bf16_f32 v60, v61, v62
	global_load_lds_dwordx4 v[66:67], off
	v_cvt_pk_bf16_f32 v61, v63, v64
	ds_read_b128 v[62:65], v151
	ds_read_b128 v[66:69], v151 offset:2048
	ds_read_b128 v[172:175], v151 offset:4096
	ds_read_b128 v[176:179], v151 offset:6144
	ds_read_b128 v[180:183], v151 offset:8192
	ds_read_b128 v[184:187], v151 offset:10240
	ds_read_b128 v[188:191], v151 offset:12288
	ds_read_b128 v[192:195], v151 offset:14336
	v_cvt_pk_bf16_f32 v58, v57, v58
	s_setprio 1
	s_waitcnt lgkmcnt(0)
	v_mfma_f32_16x16x32_bf16 v[62:65], v[62:65], v[58:61], v[70:73]
	v_mfma_f32_16x16x32_bf16 v[66:69], v[66:69], v[58:61], v[74:77]
	v_mfma_f32_16x16x32_bf16 v[70:73], v[172:175], v[58:61], v[152:155]
	v_mfma_f32_16x16x32_bf16 v[74:77], v[176:179], v[58:61], v[156:159]
	v_mfma_f32_16x16x32_bf16 v[152:155], v[180:183], v[58:61], v[160:163]
	v_mfma_f32_16x16x32_bf16 v[156:159], v[184:187], v[58:61], v[164:167]
	v_mfma_f32_16x16x32_bf16 v[160:163], v[188:191], v[58:61], v[168:171]
	v_mfma_f32_16x16x32_bf16 v[18:21], v[192:195], v[58:61], v[18:21]
	s_setprio 0
	s_ashr_i32 s81, s80, 31
	s_lshl_b64 s[72:73], s[80:81], 9
	s_waitcnt vmcnt(8)
	v_lshl_add_u64 v[58:59], v[122:123], 0, s[72:73]
	s_mov_b32 m0, s94
	s_waitcnt lgkmcnt(0)
	s_barrier
; __device__ __forceinline__ void phase_attention(const Params& p, char* shmc) {
;     ...
;       } else {
;         const int kr = s - 8;
;         union { bf16x8 v; unsigned u[4]; } pf;
;         pf.u[0] = pack2(sc[kr][0][0], sc[kr][0][1]);
;         pf.u[1] = pack2(sc[kr][0][2], sc[kr][0][3]);
;         pf.u[2] = pack2(sc[kr][1][0], sc[kr][1][1]);
;         pf.u[3] = pack2(sc[kr][1][2], sc[kr][1][3]);
;         bf16x8 vf[8];
; #pragma unroll
;         for (int db = 0; db < 8; ++db) vf[db] = *reinterpret_cast<const bf16x8*>(slot + aV + db * 2048);
;         __builtin_amdgcn_s_setprio(1);
; #pragma unroll
;         for (int db = 0; db < 8; ++db) o[db] = __builtin_amdgcn_mfma_f32_16x16x32_bf16(vf[db], pf.v, o[db], 0, 0, 0);
;         __builtin_amdgcn_s_setprio(0);
	global_load_lds_dwordx4 v[58:59], off
	v_lshl_add_u64 v[60:61], v[58:59], 0, s[48:49]
	s_mov_b32 m0, s95
	v_cvt_pk_bf16_f32 v51, v51, v52
	global_load_lds_dwordx4 v[60:61], off
	v_lshl_add_u64 v[60:61], v[58:59], 0, s[52:53]
	s_mov_b32 m0, s96
	v_lshl_add_u64 v[58:59], v[58:59], 0, s[54:55]
	global_load_lds_dwordx4 v[60:61], off
	s_mov_b32 m0, s97
	v_cvt_pk_bf16_f32 v52, v53, v54
	global_load_lds_dwordx4 v[58:59], off
	v_cvt_pk_bf16_f32 v53, v55, v56
	ds_read_b128 v[54:57], v149
	ds_read_b128 v[58:61], v149 offset:2048
	ds_read_b128 v[164:167], v149 offset:4096
	ds_read_b128 v[168:171], v149 offset:6144
	ds_read_b128 v[172:175], v149 offset:8192
	ds_read_b128 v[176:179], v149 offset:10240
	ds_read_b128 v[180:183], v149 offset:12288
	ds_read_b128 v[184:187], v149 offset:14336
	v_cvt_pk_bf16_f32 v50, v49, v50
	s_setprio 1
	s_waitcnt lgkmcnt(0)
	v_mfma_f32_16x16x32_bf16 v[54:57], v[54:57], v[50:53], v[62:65]
	v_mfma_f32_16x16x32_bf16 v[58:61], v[58:61], v[50:53], v[66:69]
	v_mfma_f32_16x16x32_bf16 v[62:65], v[164:167], v[50:53], v[70:73]
	v_mfma_f32_16x16x32_bf16 v[66:69], v[168:171], v[50:53], v[74:77]
	v_mfma_f32_16x16x32_bf16 v[70:73], v[172:175], v[50:53], v[152:155]
	v_mfma_f32_16x16x32_bf16 v[74:77], v[176:179], v[50:53], v[156:159]
	v_mfma_f32_16x16x32_bf16 v[152:155], v[180:183], v[50:53], v[160:163]
	v_mfma_f32_16x16x32_bf16 v[18:21], v[184:187], v[50:53], v[18:21]
	s_setprio 0
	s_add_i32 s90, s91, s90
	s_ashr_i32 s91, s90, 31
	s_lshl_b64 s[72:73], s[90:91], 9
	s_waitcnt vmcnt(8)
	v_lshl_add_u64 v[50:51], v[22:23], 0, s[72:73]
	s_mov_b32 m0, s93
	s_waitcnt lgkmcnt(0)
	s_barrier
	global_load_lds_dwordx4 v[50:51], off
	v_lshl_add_u64 v[52:53], v[50:51], 0, s[38:39]
	s_mov_b32 m0, s68
	v_cvt_pk_bf16_f32 v43, v43, v44
	global_load_lds_dwordx4 v[52:53], off
	v_lshl_add_u64 v[52:53], v[50:51], 0, s[40:41]
	s_mov_b32 m0, s13
	v_lshl_add_u64 v[50:51], v[50:51], 0, s[42:43]
	global_load_lds_dwordx4 v[52:53], off
	s_mov_b32 m0, s2
	v_cvt_pk_bf16_f32 v44, v45, v46
	global_load_lds_dwordx4 v[50:51], off
	v_cvt_pk_bf16_f32 v45, v47, v48
	ds_read_b128 v[46:49], v149 offset:32768
	ds_read_b128 v[50:53], v149 offset:34816
	ds_read_b128 v[156:159], v149 offset:36864
	ds_read_b128 v[160:163], v149 offset:38912
	ds_read_b128 v[164:167], v149 offset:40960
	ds_read_b128 v[168:171], v149 offset:43008
	ds_read_b128 v[172:175], v149 offset:45056
	ds_read_b128 v[176:179], v149 offset:47104
	v_cvt_pk_bf16_f32 v42, v41, v42
	s_setprio 1
	s_waitcnt lgkmcnt(0)
	v_mfma_f32_16x16x32_bf16 v[46:49], v[46:49], v[42:45], v[54:57]
	v_mfma_f32_16x16x32_bf16 v[50:53], v[50:53], v[42:45], v[58:61]
	v_mfma_f32_16x16x32_bf16 v[54:57], v[156:159], v[42:45], v[62:65]
	v_mfma_f32_16x16x32_bf16 v[58:61], v[160:163], v[42:45], v[66:69]
	v_mfma_f32_16x16x32_bf16 v[62:65], v[164:167], v[42:45], v[70:73]
	v_mfma_f32_16x16x32_bf16 v[66:69], v[168:171], v[42:45], v[74:77]
	v_mfma_f32_16x16x32_bf16 v[70:73], v[172:175], v[42:45], v[152:155]
	v_mfma_f32_16x16x32_bf16 v[18:21], v[176:179], v[42:45], v[18:21]
	s_setprio 0
	s_add_i32 s72, s90, 64
	s_ashr_i32 s73, s72, 31
	s_lshl_b64 s[72:73], s[72:73], 9
	s_waitcnt vmcnt(8)
	v_lshl_add_u64 v[42:43], v[22:23], 0, s[72:73]
	s_mov_b32 m0, s14
	s_waitcnt lgkmcnt(0)
	s_barrier
	global_load_lds_dwordx4 v[42:43], off
	v_lshl_add_u64 v[44:45], v[42:43], 0, s[38:39]
	s_mov_b32 m0, s69
	v_cvt_pk_bf16_f32 v35, v35, v36
	global_load_lds_dwordx4 v[44:45], off
	v_lshl_add_u64 v[44:45], v[42:43], 0, s[40:41]
	s_mov_b32 m0, s70
	v_lshl_add_u64 v[42:43], v[42:43], 0, s[42:43]
	global_load_lds_dwordx4 v[44:45], off
	s_mov_b32 m0, s76
	v_cvt_pk_bf16_f32 v36, v37, v38
	global_load_lds_dwordx4 v[42:43], off
	v_cvt_pk_bf16_f32 v37, v39, v40
	ds_read_b128 v[38:41], v150
	ds_read_b128 v[42:45], v150 offset:2048
	ds_read_b128 v[74:77], v150 offset:4096
	ds_read_b128 v[152:155], v150 offset:6144
	ds_read_b128 v[156:159], v150 offset:8192
	ds_read_b128 v[160:163], v150 offset:10240
	ds_read_b128 v[164:167], v150 offset:12288
	ds_read_b128 v[168:171], v150 offset:14336
	v_cvt_pk_bf16_f32 v34, v33, v34
	s_setprio 1
	s_waitcnt lgkmcnt(0)
	v_mfma_f32_16x16x32_bf16 v[38:41], v[38:41], v[34:37], v[46:49]
	v_mfma_f32_16x16x32_bf16 v[42:45], v[42:45], v[34:37], v[50:53]
	v_mfma_f32_16x16x32_bf16 v[46:49], v[74:77], v[34:37], v[54:57]
	v_mfma_f32_16x16x32_bf16 v[50:53], v[152:155], v[34:37], v[58:61]
	v_mfma_f32_16x16x32_bf16 v[54:57], v[156:159], v[34:37], v[62:65]
	v_mfma_f32_16x16x32_bf16 v[58:61], v[160:163], v[34:37], v[66:69]
	v_mfma_f32_16x16x32_bf16 v[62:65], v[164:167], v[34:37], v[70:73]
	v_mfma_f32_16x16x32_bf16 v[18:21], v[168:171], v[34:37], v[18:21]
	s_setprio 0
	s_add_i32 s68, s90, 0x80
	s_ashr_i32 s69, s68, 31
	s_lshl_b64 s[68:69], s[68:69], 9
	s_waitcnt vmcnt(8)
	v_lshl_add_u64 v[22:23], v[22:23], 0, s[68:69]
	s_mov_b32 m0, s34
	s_waitcnt lgkmcnt(0)
	s_barrier
; __device__ __forceinline__ void phase_attention(const Params& p, char* shmc) {
;     ...
;       } else {
;         const int kr = s - 8;
;         union { bf16x8 v; unsigned u[4]; } pf;
;         pf.u[0] = pack2(sc[kr][0][0], sc[kr][0][1]);
;         pf.u[1] = pack2(sc[kr][0][2], sc[kr][0][3]);
;         pf.u[2] = pack2(sc[kr][1][0], sc[kr][1][1]);
;         pf.u[3] = pack2(sc[kr][1][2], sc[kr][1][3]);
;         bf16x8 vf[8];
; #pragma unroll
;         for (int db = 0; db < 8; ++db) vf[db] = *reinterpret_cast<const bf16x8*>(slot + aV + db * 2048);
;         __builtin_amdgcn_s_setprio(1);
; #pragma unroll
;         for (int db = 0; db < 8; ++db) o[db] = __builtin_amdgcn_mfma_f32_16x16x32_bf16(vf[db], pf.v, o[db], 0, 0, 0);
;         __builtin_amdgcn_s_setprio(0);
;       }
;     }
;     const float inv = 1.0f / sum;
;     u16* op = O + (size_t)tq * DM + h * 128 + fq * 4;
; #pragma unroll
;     for (int db = 0; db < 8; ++db) {
;       uint2 w;
;       w.x = pack2(o[db][0] * inv, o[db][1] * inv);
;       w.y = pack2(o[db][2] * inv, o[db][3] * inv);
;       *reinterpret_cast<uint2*>(op + db * 16) = w;
;     }
	global_load_lds_dwordx4 v[22:23], off
	v_lshl_add_u64 v[34:35], v[22:23], 0, s[38:39]
	s_mov_b32 m0, s35
	v_cvt_pk_bf16_f32 v27, v27, v28
	global_load_lds_dwordx4 v[34:35], off
	v_lshl_add_u64 v[34:35], v[22:23], 0, s[40:41]
	s_mov_b32 m0, s6
	v_lshl_add_u64 v[22:23], v[22:23], 0, s[42:43]
	global_load_lds_dwordx4 v[34:35], off
	s_mov_b32 m0, s7
	v_cvt_pk_bf16_f32 v28, v29, v30
	global_load_lds_dwordx4 v[22:23], off
	v_cvt_pk_bf16_f32 v29, v31, v32
	ds_read_b128 v[30:33], v151
	ds_read_b128 v[34:37], v151 offset:2048
	ds_read_b128 v[66:69], v151 offset:4096
	ds_read_b128 v[70:73], v151 offset:6144
	ds_read_b128 v[74:77], v151 offset:8192
	ds_read_b128 v[152:155], v151 offset:10240
	ds_read_b128 v[156:159], v151 offset:12288
	ds_read_b128 v[160:163], v151 offset:14336
	v_cvt_pk_bf16_f32 v26, v25, v26
	s_setprio 1
	s_waitcnt lgkmcnt(0)
	v_mfma_f32_16x16x32_bf16 v[30:33], v[30:33], v[26:29], v[38:41]
	v_mfma_f32_16x16x32_bf16 v[34:37], v[34:37], v[26:29], v[42:45]
	v_mfma_f32_16x16x32_bf16 v[38:41], v[66:69], v[26:29], v[46:49]
	v_mfma_f32_16x16x32_bf16 v[42:45], v[70:73], v[26:29], v[50:53]
	v_mfma_f32_16x16x32_bf16 v[46:49], v[74:77], v[26:29], v[54:57]
	v_mfma_f32_16x16x32_bf16 v[50:53], v[152:155], v[26:29], v[58:61]
	v_mfma_f32_16x16x32_bf16 v[54:57], v[156:159], v[26:29], v[62:65]
	v_mfma_f32_16x16x32_bf16 v[18:21], v[160:163], v[26:29], v[18:21]
	s_setprio 0
	v_div_scale_f32 v23, s[68:69], v24, v24, 1.0
	v_rcp_f32_e32 v25, v23
	v_add_u32_e32 v22, s26, v130
	v_mov_b32_e32 v121, v85
	s_lshl_b32 s2, s5, 1
	v_fma_f32 v26, -v23, v25, 1.0
	v_fmac_f32_e32 v25, v26, v25
	v_div_scale_f32 v26, vcc, 1.0, v24, 1.0
	v_mul_f32_e32 v27, v26, v25
	v_fma_f32 v28, -v23, v27, v26
	v_fmac_f32_e32 v27, v28, v25
	v_fma_f32 v23, -v23, v27, v26
	v_div_fmas_f32 v23, v23, v25, v27
	v_div_fixup_f32 v24, v23, v24, 1.0
	v_ashrrev_i32_e32 v23, 31, v22
	v_lshlrev_b64 v[22:23], 12, v[22:23]
	v_add_lshl_u32 v26, s71, v81, 7
	v_lshl_add_u64 v[22:23], s[8:9], 0, v[22:23]
	v_ashrrev_i32_e32 v27, 31, v26
	v_lshl_add_u64 v[22:23], v[26:27], 1, v[22:23]
	v_pk_mul_f32 v[26:27], v[30:31], v[24:25] op_sel_hi:[1,0]
	v_pk_mul_f32 v[28:29], v[32:33], v[24:25] op_sel_hi:[1,0]
	v_lshl_add_u64 v[22:23], v[22:23], 0, v[120:121]
	v_cvt_pk_bf16_f32 v26, v26, v27
	v_cvt_pk_bf16_f32 v27, v28, v29
	global_store_dwordx2 v[22:23], v[26:27], off
	v_pk_mul_f32 v[26:27], v[34:35], v[24:25] op_sel_hi:[1,0]
	v_pk_mul_f32 v[28:29], v[36:37], v[24:25] op_sel_hi:[1,0]
	v_cvt_pk_bf16_f32 v26, v26, v27
	v_cvt_pk_bf16_f32 v27, v28, v29
	global_store_dwordx2 v[22:23], v[26:27], off offset:32
	v_pk_mul_f32 v[26:27], v[38:39], v[24:25] op_sel_hi:[1,0]
	v_pk_mul_f32 v[28:29], v[40:41], v[24:25] op_sel_hi:[1,0]
	v_cvt_pk_bf16_f32 v26, v26, v27
	v_cvt_pk_bf16_f32 v27, v28, v29
	global_store_dwordx2 v[22:23], v[26:27], off offset:64
	v_pk_mul_f32 v[26:27], v[42:43], v[24:25] op_sel_hi:[1,0]
	v_pk_mul_f32 v[28:29], v[44:45], v[24:25] op_sel_hi:[1,0]
	v_cvt_pk_bf16_f32 v26, v26, v27
	v_cvt_pk_bf16_f32 v27, v28, v29
	global_store_dwordx2 v[22:23], v[26:27], off offset:96
	v_pk_mul_f32 v[26:27], v[46:47], v[24:25] op_sel_hi:[1,0]
	v_pk_mul_f32 v[28:29], v[48:49], v[24:25] op_sel_hi:[1,0]
	v_cvt_pk_bf16_f32 v26, v26, v27
	v_cvt_pk_bf16_f32 v27, v28, v29
	global_store_dwordx2 v[22:23], v[26:27], off offset:128
	v_pk_mul_f32 v[26:27], v[50:51], v[24:25] op_sel_hi:[1,0]
	v_pk_mul_f32 v[28:29], v[52:53], v[24:25] op_sel_hi:[1,0]
	v_cvt_pk_bf16_f32 v26, v26, v27
	v_cvt_pk_bf16_f32 v27, v28, v29
	global_store_dwordx2 v[22:23], v[26:27], off offset:160
	v_pk_mul_f32 v[26:27], v[54:55], v[24:25] op_sel_hi:[1,0]
	v_pk_mul_f32 v[28:29], v[56:57], v[24:25] op_sel_hi:[1,0]
	v_pk_mul_f32 v[18:19], v[18:19], v[24:25] op_sel_hi:[1,0]
	v_pk_mul_f32 v[20:21], v[20:21], v[24:25] op_sel_hi:[1,0]
	v_cvt_pk_bf16_f32 v26, v26, v27
	v_cvt_pk_bf16_f32 v27, v28, v29
	v_cvt_pk_bf16_f32 v18, v18, v19
	v_cvt_pk_bf16_f32 v19, v20, v21
	s_cmp_eq_u32 s2, s71
	global_store_dwordx2 v[22:23], v[26:27], off offset:192
	global_store_dwordx2 v[22:23], v[18:19], off offset:224
	s_cbranch_scc1 .LBB0_814
	v_add_u32_e32 v18, s2, v81
	v_mul_lo_u32 v18, v18, s27
	s_mov_b64 s[80:81], 0
	v_mov_b32_e32 v19, v79
	v_mov_b32_e32 v20, v78
